# NSA: one static s_setprio 1 for waves 4-7 (the second wave of each SIMD) over the whole NSA task, reset at task exit
# baseline (speedup 1.0000x reference)
; __device__ __forceinline__ unsigned cvt_pk_bf16(float lo, float hi) { unsigned r; asm volatile("v_cvt_pk_bf16_f32 %0, %1, %2" : "=v"(r) : "v"(lo), "v"(hi)); return r; }
; __device__ __forceinline__ float x16sum(float x) { auto r = __builtin_amdgcn_permlane16_swap(__float_as_uint(x), __float_as_uint(x), false, false); return __uint_as_float(r[0]) + __uint_as_float(r[1]); }
; __device__ __forceinline__ float x32sum(float x) { auto r = __builtin_amdgcn_permlane32_swap(__float_as_uint(x), __float_as_uint(x), false, false); return __uint_as_float(r[0]) + __uint_as_float(r[1]); }
; __device__ __forceinline__ int fresh_lane() { unsigned m_ = ~0u; asm volatile("" : "+s"(m_)); return (int)__builtin_amdgcn_mbcnt_hi(m_, __builtin_amdgcn_mbcnt_lo(m_, 0u)); }
; __device__ __forceinline__ void nsa_wg_task(bf16_t* zb, const bf16_t* kcb, const bf16_t* vctb, const bf16_t* vst, const bf16_t* vwt, int g, int T0, float* accb, LAS unsigned char* lds, int wave, int lane, int tid) {
;     ...
;     asm volatile("s_waitcnt vmcnt(0)" ::: "memory"); __builtin_amdgcn_s_barrier(); asm volatile("" ::: "memory");
;     ...
; #pragma unroll
;     for (int r = 0; r < 2; ++r) { l[r] = x16sum(l[r]); l[r] = x32sum(l[r]);
;         const float sc = (l[r] > 0.f ? 1.0f / l[r] : 0.f) * gate_w[r];
; #pragma unroll
;         for (int dt = 0; dt < 4; ++dt) O[r][dt] = *(const f32x4*)(accb + (size_t)t[r] * 1024 + (g * 4 + h) * 64 + dt * 16 + 4 * fq) + O[r][dt] * sc;
;         bf16_t* op = zb + (size_t)t[r] * ZM + ZC_Q + (g * 4 + h) * 64 + 4 * fq;
; #pragma unroll
;         for (int dt = 0; dt < 4; ++dt) { u32x2 w; w.x = cvt_pk_bf16(O[r][dt][0], O[r][dt][1]); w.y = cvt_pk_bf16(O[r][dt][2], O[r][dt][3]); *(u32x2*)(op + dt * 16) = w; } }
; __global__ void __launch_bounds__(512, 2) mega(Args a) {
;     ...
;             for (int wt = cb; wt < (SEQ / 64) * 4; wt += G) { const int gg = wt & 3; int tl = wt >> 2;
;                 if (G == 256) { const int j = cb >> 2, r = wt >> 8; tl = r == 0 ? j : 127 - j; }
;                 const int T0 = tl * 64;
;                 const int ln_ = fresh_lane(); nsa_wg_task(ZMAIN, KC, VCT, VST, VWT, gg, T0, MF, lds, wave, ln_, (wave << 6) | ln_); }
.LBB0_148:
	s_waitcnt vmcnt(0)
	v_lshlrev_b32_e32 v0, 16, v190
	v_mul_f32_e32 v0, 0xbfb8aa3b, v0
	v_exp_f32_e32 v0, v0
	s_waitcnt vmcnt(0)
	s_barrier
	v_add_f32_e32 v0, 1.0, v0
	s_waitcnt lgkmcnt(0)
	v_rcp_f32_e32 v24, v0
	v_lshlrev_b32_e32 v0, 16, v188
	v_mul_f32_e32 v0, 0xbfb8aa3b, v0
	v_exp_f32_e32 v0, v0
	s_add_i32 s49, s49, s35
	s_cmpk_gt_i32 s49, 0x1ff
	v_add_f32_e32 v0, 1.0, v0
	v_rcp_f32_e32 v2, v0
	v_lshl_add_u64 v[0:1], v[170:171], 2, s[36:37]
	v_lshl_add_u64 v[4:5], v[166:167], 2, v[0:1]
	v_mov_b32_e32 v0, v172
	s_nop 1
	v_permlane16_swap_b32_e32 v172, v0
	v_add_f32_e32 v0, v172, v0
	v_mov_b32_e32 v1, v0
	s_nop 1
	v_permlane32_swap_b32_e32 v0, v1
	v_add_f32_e32 v0, v0, v1
	v_div_scale_f32 v1, s[0:1], v0, v0, 1.0
	v_rcp_f32_e32 v3, v1
	v_cmp_lt_f32_e64 s[4:5], 0, v0
	v_fma_f32 v6, -v1, v3, 1.0
	v_fmac_f32_e32 v3, v6, v3
	v_div_scale_f32 v6, vcc, 1.0, v0, 1.0
	v_mul_f32_e32 v7, v6, v3
	v_fma_f32 v8, -v1, v7, v6
	v_fmac_f32_e32 v7, v8, v3
	v_fma_f32 v1, -v1, v7, v6
	v_div_fmas_f32 v1, v1, v3, v7
	v_div_fixup_f32 v0, v1, v0, 1.0
	v_cndmask_b32_e64 v0, 0, v0, s[4:5]
	v_lshl_add_u64 v[8:9], v[4:5], 0, v[168:169]
	v_mul_f32_e32 v6, v2, v0
	global_load_dwordx4 v[0:3], v[8:9], off
	v_lshl_add_u64 v[4:5], v[4:5], 0, v[162:163]
	s_waitcnt vmcnt(0)
	v_pk_fma_f32 v[10:11], v[114:115], v[6:7], v[2:3] op_sel_hi:[1,0,1]
	v_pk_fma_f32 v[12:13], v[112:113], v[6:7], v[0:1] op_sel_hi:[1,0,1]
	global_load_dwordx4 v[0:3], v[8:9], off offset:64
	s_waitcnt vmcnt(0)
	v_pk_fma_f32 v[14:15], v[110:111], v[6:7], v[2:3] op_sel_hi:[1,0,1]
	v_pk_fma_f32 v[16:17], v[108:109], v[6:7], v[0:1] op_sel_hi:[1,0,1]
	global_load_dwordx4 v[0:3], v[8:9], off offset:128
	s_waitcnt vmcnt(0)
	v_pk_fma_f32 v[18:19], v[106:107], v[6:7], v[2:3] op_sel_hi:[1,0,1]
	v_pk_fma_f32 v[20:21], v[104:105], v[6:7], v[0:1] op_sel_hi:[1,0,1]
	global_load_dwordx4 v[0:3], v[8:9], off offset:192
	v_cvt_pk_bf16_f32 v12, v12, v13
	v_cvt_pk_bf16_f32 v13, v10, v11
	s_waitcnt vmcnt(0)
	v_pk_fma_f32 v[8:9], v[102:103], v[6:7], v[2:3] op_sel_hi:[1,0,1]
	v_pk_fma_f32 v[6:7], v[100:101], v[6:7], v[0:1] op_sel_hi:[1,0,1]
	v_lshlrev_b64 v[0:1], 1, v[170:171]
	v_lshl_add_u64 v[22:23], v[156:157], 0, v[0:1]
	v_lshlrev_b64 v[2:3], 1, v[166:167]
	v_lshl_add_u64 v[22:23], v[22:23], 0, v[2:3]
	global_store_dwordx2 v[22:23], v[12:13], off offset:2048
	v_cvt_pk_bf16_f32 v10, v16, v17
	v_cvt_pk_bf16_f32 v11, v14, v15
	global_store_dwordx2 v[22:23], v[10:11], off offset:2080
	v_cvt_pk_bf16_f32 v10, v20, v21
	v_cvt_pk_bf16_f32 v11, v18, v19
	global_store_dwordx2 v[22:23], v[10:11], off offset:2112
	v_cvt_pk_bf16_f32 v6, v6, v7
	v_cvt_pk_bf16_f32 v7, v8, v9
	global_store_dwordx2 v[22:23], v[6:7], off offset:2144
	v_mov_b32_e32 v6, v173
	s_nop 1
	v_permlane16_swap_b32_e32 v173, v6
	v_add_f32_e32 v6, v173, v6
	v_mov_b32_e32 v7, v6
	s_nop 1
	v_permlane32_swap_b32_e32 v6, v7
	v_add_f32_e32 v6, v6, v7
	v_div_scale_f32 v7, s[0:1], v6, v6, 1.0
	v_rcp_f32_e32 v8, v7
	v_cmp_lt_f32_e64 s[4:5], 0, v6
	v_lshl_add_u64 v[0:1], v[66:67], 0, v[0:1]
	v_lshl_add_u64 v[0:1], v[0:1], 0, v[2:3]
	v_fma_f32 v9, -v7, v8, 1.0
	v_fmac_f32_e32 v8, v9, v8
	v_div_scale_f32 v9, vcc, 1.0, v6, 1.0
	v_mul_f32_e32 v10, v9, v8
	v_fma_f32 v11, -v7, v10, v9
	v_fmac_f32_e32 v10, v11, v8
	v_fma_f32 v7, -v7, v10, v9
	v_div_fmas_f32 v7, v7, v8, v10
	global_load_dwordx4 v[8:11], v[4:5], off
	v_div_fixup_f32 v6, v7, v6, 1.0
	v_cndmask_b32_e64 v6, 0, v6, s[4:5]
	v_mul_f32_e32 v6, v24, v6
	s_waitcnt vmcnt(0)
	v_pk_fma_f32 v[12:13], v[98:99], v[6:7], v[10:11] op_sel_hi:[1,0,1]
	v_pk_fma_f32 v[14:15], v[96:97], v[6:7], v[8:9] op_sel_hi:[1,0,1]
	global_load_dwordx4 v[8:11], v[4:5], off offset:64
	s_waitcnt vmcnt(0)
	v_pk_fma_f32 v[16:17], v[94:95], v[6:7], v[10:11] op_sel_hi:[1,0,1]
	v_pk_fma_f32 v[18:19], v[92:93], v[6:7], v[8:9] op_sel_hi:[1,0,1]
	global_load_dwordx4 v[8:11], v[4:5], off offset:128
	s_waitcnt vmcnt(0)
	v_pk_fma_f32 v[20:21], v[90:91], v[6:7], v[10:11] op_sel_hi:[1,0,1]
	v_pk_fma_f32 v[22:23], v[88:89], v[6:7], v[8:9] op_sel_hi:[1,0,1]
	global_load_dwordx4 v[8:11], v[4:5], off offset:192
	v_cvt_pk_bf16_f32 v2, v14, v15
	v_cvt_pk_bf16_f32 v3, v12, v13
	global_store_dwordx2 v[0:1], v[2:3], off offset:2048
	v_cvt_pk_bf16_f32 v2, v18, v19
	v_cvt_pk_bf16_f32 v3, v16, v17
	global_store_dwordx2 v[0:1], v[2:3], off offset:2080
	v_cvt_pk_bf16_f32 v2, v22, v23
	v_cvt_pk_bf16_f32 v3, v20, v21
	global_store_dwordx2 v[0:1], v[2:3], off offset:2112
	s_waitcnt vmcnt(3)
	v_pk_fma_f32 v[4:5], v[86:87], v[6:7], v[10:11] op_sel_hi:[1,0,1]
	v_pk_fma_f32 v[6:7], v[84:85], v[6:7], v[8:9] op_sel_hi:[1,0,1]
	s_nop 0
	v_cvt_pk_bf16_f32 v2, v6, v7
	v_cvt_pk_bf16_f32 v3, v4, v5
	global_store_dwordx2 v[0:1], v[2:3], off offset:2144
	s_setprio 0
	s_cbranch_scc1 .LBB0_351
.LBB0_149:
	s_cmp_lt_u32 s15, 32
	s_cbranch_scc1 .Lnsa_prio_skip
	s_setprio 1
